# P3 scan: each step's first S^T fragment ds_read issued right after the publishing barrier (ahead of the operand prefetch block)
# speedup vs baseline: 1.0096x; 1.0096x over previous
.LBB0_888:
	ds_read_b128 v[246:249], v237
	v_lshl_add_u64 v[214:215], s[8:9], 0, v[196:197]
	v_add_co_u32_e32 v98, vcc, s25, v214
	v_lshl_add_u64 v[216:217], s[8:9], 0, v[198:199]
	s_nop 0
	v_addc_co_u32_e32 v99, vcc, 0, v215, vcc
	v_add_co_u32_e32 v102, vcc, s26, v214
	v_lshl_add_u64 v[218:219], s[8:9], 0, v[200:201]
	s_nop 0
	v_addc_co_u32_e32 v103, vcc, 0, v215, vcc
	v_add_co_u32_e32 v106, vcc, s25, v216
	v_lshl_add_u64 v[220:221], s[8:9], 0, v[202:203]
	s_nop 0
	v_addc_co_u32_e32 v107, vcc, 0, v217, vcc
	v_add_co_u32_e32 v110, vcc, s26, v216
	v_lshl_add_u64 v[222:223], s[8:9], 0, v[194:195]
	s_nop 0
	v_addc_co_u32_e32 v111, vcc, 0, v217, vcc
	v_add_co_u32_e32 v114, vcc, s25, v218
	v_lshl_add_u64 v[224:225], s[8:9], 0, v[204:205]
	s_nop 0
	v_addc_co_u32_e32 v115, vcc, 0, v219, vcc
	v_add_co_u32_e32 v118, vcc, s26, v218
	global_load_dwordx4 v[98:101], v[98:99], off
	s_nop 0
	v_addc_co_u32_e32 v119, vcc, 0, v219, vcc
	v_add_co_u32_e32 v122, vcc, s25, v220
	global_load_dwordx4 v[102:105], v[102:103], off
	s_nop 0
	v_addc_co_u32_e32 v123, vcc, 0, v221, vcc
	v_add_co_u32_e32 v126, vcc, s26, v220
	global_load_dwordx4 v[106:109], v[106:107], off
	s_nop 0
	v_addc_co_u32_e32 v127, vcc, 0, v221, vcc
	v_add_co_u32_e32 v130, vcc, s27, v222
	global_load_dwordx4 v[110:113], v[110:111], off
	s_nop 0
	v_addc_co_u32_e32 v131, vcc, 0, v223, vcc
	global_load_dwordx4 v[114:117], v[114:115], off
	v_lshl_add_u64 v[226:227], s[8:9], 0, v[206:207]
	global_load_dwordx4 v[118:121], v[118:119], off
	v_lshl_add_u64 v[228:229], s[8:9], 0, v[208:209]
	global_load_dwordx4 v[122:125], v[122:123], off
	v_lshl_add_u64 v[230:231], s[8:9], 0, v[210:211]
	global_load_dwordx4 v[126:129], v[126:127], off
	s_nop 0
	global_load_dword v241, v[130:131], off
	global_load_dword v242, v[130:131], off offset:256
	global_load_dword v243, v[130:131], off offset:512
	global_load_dword v244, v[130:131], off offset:768
	v_add_co_u32_e32 v130, vcc, s34, v224
	v_lshl_add_u64 v[232:233], s[8:9], 0, v[212:213]
	s_nop 0
	v_addc_co_u32_e32 v131, vcc, 0, v225, vcc
	v_add_co_u32_e32 v134, vcc, s34, v226
	global_load_dwordx4 v[130:133], v[130:131], off
	s_nop 0
	v_addc_co_u32_e32 v135, vcc, 0, v227, vcc
	v_add_co_u32_e32 v146, vcc, s35, v228
	global_load_dwordx4 v[134:137], v[134:135], off
	s_nop 0
	v_addc_co_u32_e32 v147, vcc, 0, v229, vcc
	v_add_co_u32_e32 v142, vcc, s35, v230
	global_load_dwordx4 v[138:141], v[146:147], off
	s_nop 0
	v_addc_co_u32_e32 v143, vcc, 0, v231, vcc
	global_load_dwordx4 v[142:145], v[142:143], off
	s_nop 0
	global_load_dwordx4 v[146:149], v[146:147], off offset:1024

	s_waitcnt vmcnt(37) lgkmcnt(0)
	v_mfma_f32_16x16x32_bf16 v[18:21], v[18:21], v[246:249], 0
	v_add_co_u32_e32 v150, vcc, s35, v232
	s_add_i32 s61, s62, 6
	s_waitcnt vmcnt(31)
	v_mfma_f32_16x16x32_bf16 v[38:41], v[38:41], v[246:249], 0
	ds_read_b128 v[246:249], v237 offset:64
	v_addc_co_u32_e32 v151, vcc, 0, v233, vcc
	s_waitcnt lgkmcnt(0)
	v_mfma_f32_16x16x32_bf16 v[6:9], v[6:9], v[246:249], v[18:21]
	global_load_dwordx4 v[150:153], v[150:151], off
	s_nop 1
	ds_read_b128 v[18:21], v237 offset:128
	s_add_i32 s65, s62, 7
	v_mfma_f32_16x16x32_bf16 v[2:5], v[2:5], v[246:249], v[38:41]
	v_readlane_b32 s64, v177, s61
	v_readlane_b32 s66, v177, s65
	s_add_i32 s63, s62, 8
	s_waitcnt vmcnt(27) lgkmcnt(0)
	v_mfma_f32_16x16x32_bf16 v[2:5], v[14:17], v[18:21], v[2:5]
	ds_read_b128 v[14:17], v237 offset:192
	v_lshl_add_u64 v[194:195], v[194:195], 0, s[16:17]
	v_lshl_add_u64 v[196:197], v[196:197], 0, s[18:19]
	s_waitcnt vmcnt(21)
	v_mfma_f32_16x16x32_bf16 v[6:9], v[26:29], v[18:21], v[6:9]
	v_mul_f32_e64 v20, v92, s64
	v_mul_f32_e64 v21, v93, s64
	v_pk_mul_f32 v[18:19], v[90:91], s[64:65] op_sel_hi:[1,0]
	v_lshl_add_u64 v[198:199], v[198:199], 0, s[18:19]
	s_waitcnt vmcnt(19) lgkmcnt(0)
	v_mfma_f32_16x16x32_bf16 v[6:9], v[22:25], v[14:17], v[6:9]
	v_lshl_add_u64 v[200:201], v[200:201], 0, s[18:19]
	v_lshl_add_u64 v[202:203], v[202:203], 0, s[18:19]
	v_lshl_add_u64 v[204:205], v[204:205], 0, s[20:21]
	v_mfma_f32_16x16x32_bf16 v[2:5], v[10:13], v[14:17], v[2:5]
	v_mul_f32_e64 v16, v96, s64
	v_mul_f32_e64 v17, v97, s64
	s_nop 1
	v_sub_f32_e32 v9, v240, v9
	v_sub_f32_e32 v8, v239, v8
	v_sub_f32_e32 v7, v238, v7
	v_sub_f32_e32 v6, v193, v6
	v_cvt_pk_bf16_f32 v6, v6, v7
	v_cvt_pk_bf16_f32 v7, v8, v9
	ds_write_b64 v236, v[6:7] offset:4352
	s_waitcnt lgkmcnt(0)
	s_barrier
	ds_read_b128 v[6:9], v235 offset:4352
	ds_read_b128 v[10:13], v235 offset:4416
	v_pk_mul_f32 v[14:15], v[94:95], s[64:65] op_sel_hi:[1,0]
	s_waitcnt lgkmcnt(1)
	v_mfma_f32_16x16x32_bf16 v[2:5], v[86:89], v[6:9], v[2:5]
	v_ashrrev_i32_e32 v193, 31, v192
	s_add_i32 s64, s62, 9
	s_add_i32 s65, s62, 10
	v_mfma_f32_16x16x32_bf16 v[14:17], v[70:73], v[6:9], v[14:17]
	v_readlane_b32 s64, v177, s64
	s_add_i32 s62, s62, 11
	v_readlane_b32 s62, v177, s62
	v_mfma_f32_16x16x32_bf16 v[6:9], v[66:69], v[6:9], v[18:21]
	v_lshl_add_u64 v[206:207], v[206:207], 0, s[20:21]
	v_lshl_add_u64 v[208:209], v[208:209], 0, s[18:19]
	v_lshl_add_u64 v[210:211], v[210:211], 0, s[18:19]
	s_waitcnt lgkmcnt(0)
	v_mfma_f32_16x16x32_bf16 v[90:93], v[82:85], v[10:13], v[14:17]
	v_lshl_add_u64 v[212:213], v[212:213], 0, s[18:19]
	s_cmp_lt_u32 s61, 24
	v_mfma_f32_16x16x32_bf16 v[94:97], v[78:81], v[10:13], v[6:9]
	v_mfma_f32_16x16x32_bf16 v[2:5], v[74:77], v[10:13], v[2:5]
	s_nop 3
	v_cvt_pk_bf16_f32 v6, v90, v91
	v_cvt_pk_bf16_f32 v7, v92, v93
	s_nop 0
	v_cvt_pk_bf16_f32 v8, v94, v95
	v_cvt_pk_bf16_f32 v9, v96, v97
	ds_write2_b64 v234, v[6:7], v[8:9] offset1:4
	v_lshlrev_b64 v[6:7], 12, v[192:193]
	v_lshl_add_u64 v[6:7], v[190:191], 0, v[6:7]
	v_add_co_u32_e32 v8, vcc, s30, v6
	global_store_dword v[6:7], v2, off
	s_nop 0
	v_addc_co_u32_e32 v9, vcc, 0, v7, vcc
	v_add_co_u32_e32 v2, vcc, s31, v6
	global_store_dword v[8:9], v3, off offset:-4096
	global_store_dword v[8:9], v4, off
	v_addc_co_u32_e32 v3, vcc, 0, v7, vcc
	global_store_dword v[2:3], v5, off
	v_add_co_u32_e32 v2, vcc, s36, v214
	s_waitcnt lgkmcnt(0)
	s_barrier
	ds_read_b128 v[246:249], v237
	s_nop 0
	v_addc_co_u32_e32 v3, vcc, 0, v215, vcc
	v_add_co_u32_e32 v6, vcc, s37, v214
	global_load_dwordx4 v[2:5], v[2:3], off
	s_nop 0
	v_addc_co_u32_e32 v7, vcc, 0, v215, vcc
	v_add_co_u32_e32 v10, vcc, s36, v216
	global_load_dwordx4 v[6:9], v[6:7], off
	s_nop 0
	v_addc_co_u32_e32 v11, vcc, 0, v217, vcc
	v_add_co_u32_e32 v14, vcc, s37, v216
	global_load_dwordx4 v[10:13], v[10:11], off
	s_nop 0
	v_addc_co_u32_e32 v15, vcc, 0, v217, vcc
	v_add_co_u32_e32 v18, vcc, s36, v218
	global_load_dwordx4 v[14:17], v[14:15], off
	s_nop 0
	v_addc_co_u32_e32 v19, vcc, 0, v219, vcc
	v_add_co_u32_e32 v22, vcc, s37, v218
	global_load_dwordx4 v[18:21], v[18:19], off
	s_nop 0
	v_addc_co_u32_e32 v23, vcc, 0, v219, vcc
	v_add_co_u32_e32 v26, vcc, s36, v220
	global_load_dwordx4 v[22:25], v[22:23], off
	s_nop 0
	v_addc_co_u32_e32 v27, vcc, 0, v221, vcc
	v_add_co_u32_e32 v38, vcc, s37, v220
	global_load_dwordx4 v[26:29], v[26:27], off
	s_nop 0
	v_addc_co_u32_e32 v39, vcc, 0, v221, vcc
	v_add_co_u32_e32 v66, vcc, s38, v222
	global_load_dwordx4 v[38:41], v[38:39], off
	s_nop 0
	v_addc_co_u32_e32 v67, vcc, 0, v223, vcc
	global_load_dword v193, v[66:67], off
	global_load_dword v238, v[66:67], off offset:256
	global_load_dword v239, v[66:67], off offset:512
	global_load_dword v240, v[66:67], off offset:768
	v_add_co_u32_e32 v66, vcc, s39, v224
	s_nop 1
	v_addc_co_u32_e32 v67, vcc, 0, v225, vcc
	v_add_co_u32_e32 v70, vcc, s39, v226
	global_load_dwordx4 v[66:69], v[66:67], off
	s_nop 0
	v_addc_co_u32_e32 v71, vcc, 0, v227, vcc
	v_add_co_u32_e32 v82, vcc, s40, v228
	global_load_dwordx4 v[74:77], v[70:71], off
	s_nop 0
	v_addc_co_u32_e32 v83, vcc, 0, v229, vcc
	v_add_co_u32_e32 v78, vcc, s40, v230
	global_load_dwordx4 v[70:73], v[82:83], off
	s_nop 0
	v_addc_co_u32_e32 v79, vcc, 0, v231, vcc
	global_load_dwordx4 v[78:81], v[78:79], off
	s_nop 0
	global_load_dwordx4 v[82:85], v[82:83], off offset:1024

	s_waitcnt lgkmcnt(0)
	v_mfma_f32_16x16x32_bf16 v[30:33], v[30:33], v[246:249], 0
	v_add_co_u32_e32 v86, vcc, s40, v232
	v_mfma_f32_16x16x32_bf16 v[34:37], v[34:37], v[246:249], 0
	ds_read_b128 v[246:249], v237 offset:64
	v_addc_co_u32_e32 v87, vcc, 0, v233, vcc
	s_waitcnt lgkmcnt(0)
	v_mfma_f32_16x16x32_bf16 v[30:33], v[46:49], v[246:249], v[30:33]
	ds_read_b128 v[46:49], v237 offset:128
	global_load_dwordx4 v[86:89], v[86:87], off
	s_waitcnt lgkmcnt(0)
	v_mfma_f32_16x16x32_bf16 v[30:33], v[42:45], v[46:49], v[30:33]
	ds_read_b128 v[42:45], v237 offset:192
	v_mfma_f32_16x16x32_bf16 v[34:37], v[50:53], v[246:249], v[34:37]
	v_mul_f32_e64 v52, v96, s66
	v_mul_f32_e64 v53, v97, s66
	v_pk_mul_f32 v[50:51], v[94:95], s[66:67] op_sel_hi:[1,0]
	s_waitcnt lgkmcnt(0)
	v_mfma_f32_16x16x32_bf16 v[30:33], v[58:61], v[42:45], v[30:33]
	v_mfma_f32_16x16x32_bf16 v[34:37], v[54:57], v[46:49], v[34:37]
	v_mul_f32_e64 v48, v92, s66
	v_mul_f32_e64 v49, v93, s66
	s_nop 4
	v_sub_f32_e32 v33, v156, v33
	v_sub_f32_e32 v32, v155, v32
	v_sub_f32_e32 v31, v154, v31
	s_waitcnt vmcnt(40)
	v_sub_f32_e32 v30, v157, v30
	v_cvt_pk_bf16_f32 v30, v30, v31
	v_cvt_pk_bf16_f32 v31, v32, v33
	ds_write_b64 v236, v[30:31] offset:4352
	s_waitcnt lgkmcnt(0)
	s_barrier
	v_mfma_f32_16x16x32_bf16 v[34:37], v[62:65], v[42:45], v[34:37]
	ds_read_b128 v[30:33], v235 offset:4352
	ds_read_b128 v[42:45], v235 offset:4416
	v_pk_mul_f32 v[46:47], v[90:91], s[66:67] op_sel_hi:[1,0]
	v_readlane_b32 s66, v177, s63
	s_waitcnt vmcnt(27) lgkmcnt(1)
	v_mfma_f32_16x16x32_bf16 v[34:37], v[130:133], v[30:33], v[34:37]
	s_waitcnt vmcnt(25)
	v_mfma_f32_16x16x32_bf16 v[46:49], v[138:141], v[30:33], v[46:49]
	s_waitcnt vmcnt(23)
	v_mfma_f32_16x16x32_bf16 v[30:33], v[146:149], v[30:33], v[50:53]
	s_waitcnt lgkmcnt(0)
	v_mfma_f32_16x16x32_bf16 v[90:93], v[142:145], v[42:45], v[46:49]
	s_waitcnt vmcnt(22)
	v_mfma_f32_16x16x32_bf16 v[94:97], v[150:153], v[42:45], v[30:33]
	v_mfma_f32_16x16x32_bf16 v[34:37], v[134:137], v[42:45], v[34:37]
	s_nop 4
	v_cvt_pk_bf16_f32 v30, v90, v91
	v_cvt_pk_bf16_f32 v31, v92, v93
	v_cvt_pk_bf16_f32 v32, v94, v95
	v_cvt_pk_bf16_f32 v33, v96, v97
	ds_write2_b64 v234, v[30:31], v[32:33] offset1:4
	v_add_u32_e32 v30, 64, v192
	v_ashrrev_i32_e32 v31, 31, v30
	v_lshlrev_b64 v[30:31], 12, v[30:31]
	v_lshl_add_u64 v[30:31], v[190:191], 0, v[30:31]
	v_add_co_u32_e32 v32, vcc, s30, v30
	global_store_dword v[30:31], v34, off
	s_nop 0
	v_addc_co_u32_e32 v33, vcc, 0, v31, vcc
	v_add_co_u32_e32 v30, vcc, s31, v30
	global_store_dword v[32:33], v35, off offset:-4096
	global_store_dword v[32:33], v36, off
	v_addc_co_u32_e32 v31, vcc, 0, v31, vcc
	global_store_dword v[30:31], v37, off
	v_add_co_u32_e32 v30, vcc, s41, v214
	s_waitcnt lgkmcnt(0)
	s_barrier
	ds_read_b128 v[154:157], v237
	s_nop 0
	v_addc_co_u32_e32 v31, vcc, 0, v215, vcc
	v_add_co_u32_e32 v34, vcc, s42, v214
	global_load_dwordx4 v[30:33], v[30:31], off
	s_nop 0
	v_addc_co_u32_e32 v35, vcc, 0, v215, vcc
	v_add_co_u32_e32 v42, vcc, s41, v216
	global_load_dwordx4 v[34:37], v[34:35], off
	s_nop 0
	v_addc_co_u32_e32 v43, vcc, 0, v217, vcc
	v_add_co_u32_e32 v46, vcc, s42, v216
	global_load_dwordx4 v[42:45], v[42:43], off
	s_nop 0
	v_addc_co_u32_e32 v47, vcc, 0, v217, vcc
	v_add_co_u32_e32 v50, vcc, s41, v218
	global_load_dwordx4 v[46:49], v[46:47], off
	s_nop 0
	v_addc_co_u32_e32 v51, vcc, 0, v219, vcc
	v_add_co_u32_e32 v54, vcc, s42, v218
	global_load_dwordx4 v[50:53], v[50:51], off
	s_nop 0
	v_addc_co_u32_e32 v55, vcc, 0, v219, vcc
	v_add_co_u32_e32 v58, vcc, s41, v220
	global_load_dwordx4 v[54:57], v[54:55], off
	s_nop 0
	v_addc_co_u32_e32 v59, vcc, 0, v221, vcc
	v_add_co_u32_e32 v62, vcc, s42, v220
	global_load_dwordx4 v[58:61], v[58:59], off
	s_nop 0
	v_addc_co_u32_e32 v63, vcc, 0, v221, vcc
	v_add_co_u32_e32 v130, vcc, s43, v222
	global_load_dwordx4 v[62:65], v[62:63], off
	s_nop 0
	v_addc_co_u32_e32 v131, vcc, 0, v223, vcc
	global_load_dword v245, v[130:131], off
	global_load_dword v246, v[130:131], off offset:256
	global_load_dword v247, v[130:131], off offset:512
	global_load_dword v248, v[130:131], off offset:768
	v_add_co_u32_e32 v130, vcc, s44, v224
	s_nop 1
	v_addc_co_u32_e32 v131, vcc, 0, v225, vcc
	v_add_co_u32_e32 v134, vcc, s44, v226
	global_load_dwordx4 v[130:133], v[130:131], off
	s_nop 0
	v_addc_co_u32_e32 v135, vcc, 0, v227, vcc
	v_add_co_u32_e32 v146, vcc, s45, v228
	global_load_dwordx4 v[138:141], v[134:135], off
	s_nop 0
	v_addc_co_u32_e32 v147, vcc, 0, v229, vcc
	v_add_co_u32_e32 v142, vcc, s45, v230
	global_load_dwordx4 v[134:137], v[146:147], off
	s_nop 0
	v_addc_co_u32_e32 v143, vcc, 0, v231, vcc
	global_load_dwordx4 v[142:145], v[142:143], off
	s_nop 0
	global_load_dwordx4 v[146:149], v[146:147], off offset:1024

	s_waitcnt lgkmcnt(0)
	v_mfma_f32_16x16x32_bf16 v[98:101], v[98:101], v[154:157], 0
	v_add_co_u32_e32 v150, vcc, s45, v232
	v_mfma_f32_16x16x32_bf16 v[102:105], v[102:105], v[154:157], 0
	ds_read_b128 v[154:157], v237 offset:64
	v_addc_co_u32_e32 v151, vcc, 0, v233, vcc
	s_waitcnt lgkmcnt(0)
	v_mfma_f32_16x16x32_bf16 v[98:101], v[106:109], v[154:157], v[98:101]
	ds_read_b128 v[106:109], v237 offset:128
	global_load_dwordx4 v[150:153], v[150:151], off
	v_mfma_f32_16x16x32_bf16 v[102:105], v[110:113], v[154:157], v[102:105]
	s_waitcnt lgkmcnt(0)
	v_mfma_f32_16x16x32_bf16 v[98:101], v[114:117], v[106:109], v[98:101]
	v_mfma_f32_16x16x32_bf16 v[102:105], v[118:121], v[106:109], v[102:105]
	ds_read_b128 v[106:109], v237 offset:192
	s_waitcnt lgkmcnt(0)
	v_mfma_f32_16x16x32_bf16 v[98:101], v[122:125], v[106:109], v[98:101]
	v_mfma_f32_16x16x32_bf16 v[102:105], v[126:129], v[106:109], v[102:105]
	s_nop 6
	v_sub_f32_e32 v101, v244, v101
	v_sub_f32_e32 v100, v243, v100
	v_sub_f32_e32 v99, v242, v99
	v_sub_f32_e32 v98, v241, v98
	v_cvt_pk_bf16_f32 v98, v98, v99
	v_cvt_pk_bf16_f32 v99, v100, v101
	ds_write_b64 v236, v[98:99] offset:4352
	s_waitcnt lgkmcnt(0)
	s_barrier
	ds_read_b128 v[98:101], v235 offset:4352
	ds_read_b128 v[106:109], v235 offset:4416
	s_waitcnt vmcnt(27) lgkmcnt(1)
	v_mfma_f32_16x16x32_bf16 v[66:69], v[66:69], v[98:101], v[102:105]
	s_waitcnt vmcnt(26) lgkmcnt(0)
	v_mfma_f32_16x16x32_bf16 v[66:69], v[74:77], v[106:109], v[66:69]
	v_mul_f32_e64 v76, v92, s66
	v_mul_f32_e64 v77, v93, s66
	v_pk_mul_f32 v[74:75], v[90:91], s[66:67] op_sel_hi:[1,0]
	v_pk_mul_f32 v[92:93], v[96:97], s[66:67] op_sel_hi:[1,0]
	v_pk_mul_f32 v[90:91], v[94:95], s[66:67] op_sel_hi:[1,0]
	s_waitcnt vmcnt(25)
	v_mfma_f32_16x16x32_bf16 v[70:73], v[70:73], v[98:101], v[74:77]
	s_waitcnt vmcnt(24)
	v_mfma_f32_16x16x32_bf16 v[122:125], v[78:81], v[106:109], v[70:73]
	s_waitcnt vmcnt(23)
	v_mfma_f32_16x16x32_bf16 v[70:73], v[82:85], v[98:101], v[90:93]
	s_waitcnt vmcnt(22)
	v_mfma_f32_16x16x32_bf16 v[126:129], v[86:89], v[106:109], v[70:73]
	s_nop 5
	v_cvt_pk_bf16_f32 v70, v122, v123
	v_cvt_pk_bf16_f32 v71, v124, v125
	v_cvt_pk_bf16_f32 v72, v126, v127
	v_cvt_pk_bf16_f32 v73, v128, v129
	ds_write2_b64 v234, v[70:71], v[72:73] offset1:4
	v_add_u32_e32 v70, 0x80, v192
	v_ashrrev_i32_e32 v71, 31, v70
	v_lshlrev_b64 v[70:71], 12, v[70:71]
	v_lshl_add_u64 v[70:71], v[190:191], 0, v[70:71]
	v_add_co_u32_e32 v72, vcc, s30, v70
	global_store_dword v[70:71], v66, off
	s_nop 0
	v_addc_co_u32_e32 v73, vcc, 0, v71, vcc
	v_add_co_u32_e32 v66, vcc, s31, v70
	global_store_dword v[72:73], v67, off offset:-4096
	global_store_dword v[72:73], v68, off
	v_addc_co_u32_e32 v67, vcc, 0, v71, vcc
	global_store_dword v[66:67], v69, off
	v_add_co_u32_e32 v66, vcc, s46, v214
	s_waitcnt lgkmcnt(0)
	s_barrier
	ds_read_b128 v[154:157], v237
	s_nop 0
	v_addc_co_u32_e32 v67, vcc, 0, v215, vcc
	global_load_dwordx4 v[90:93], v[66:67], off
	v_add_co_u32_e32 v66, vcc, s47, v214
	s_nop 1
	v_addc_co_u32_e32 v67, vcc, 0, v215, vcc
	global_load_dwordx4 v[94:97], v[66:67], off
	v_add_co_u32_e32 v66, vcc, s46, v216
	s_nop 1
	v_addc_co_u32_e32 v67, vcc, 0, v217, vcc
	global_load_dwordx4 v[98:101], v[66:67], off
	v_add_co_u32_e32 v66, vcc, s47, v216
	s_nop 1
	v_addc_co_u32_e32 v67, vcc, 0, v217, vcc
	global_load_dwordx4 v[102:105], v[66:67], off
	v_add_co_u32_e32 v66, vcc, s46, v218
	s_nop 1
	v_addc_co_u32_e32 v67, vcc, 0, v219, vcc
	global_load_dwordx4 v[106:109], v[66:67], off
	v_add_co_u32_e32 v66, vcc, s47, v218
	s_nop 1
	v_addc_co_u32_e32 v67, vcc, 0, v219, vcc
	global_load_dwordx4 v[110:113], v[66:67], off
	v_add_co_u32_e32 v66, vcc, s46, v220
	s_nop 1
	v_addc_co_u32_e32 v67, vcc, 0, v221, vcc
	global_load_dwordx4 v[114:117], v[66:67], off
	v_add_co_u32_e32 v66, vcc, s47, v220
	s_nop 1
	v_addc_co_u32_e32 v67, vcc, 0, v221, vcc
	global_load_dwordx4 v[118:121], v[66:67], off
	v_add_co_u32_e32 v66, vcc, s48, v222
	s_nop 1
	v_addc_co_u32_e32 v67, vcc, 0, v223, vcc
	global_load_dword v241, v[66:67], off
	global_load_dword v242, v[66:67], off offset:256
	global_load_dword v243, v[66:67], off offset:512
	global_load_dword v244, v[66:67], off offset:768
	v_add_co_u32_e32 v66, vcc, s49, v224
	s_nop 1
	v_addc_co_u32_e32 v67, vcc, 0, v225, vcc
	v_add_co_u32_e32 v70, vcc, s49, v226
	global_load_dwordx4 v[66:69], v[66:67], off
	s_nop 0
	v_addc_co_u32_e32 v71, vcc, 0, v227, vcc
	v_add_co_u32_e32 v82, vcc, s50, v228
	global_load_dwordx4 v[74:77], v[70:71], off
	s_nop 0
	v_addc_co_u32_e32 v83, vcc, 0, v229, vcc
	v_add_co_u32_e32 v78, vcc, s50, v230
	global_load_dwordx4 v[70:73], v[82:83], off
	s_nop 0
	v_addc_co_u32_e32 v79, vcc, 0, v231, vcc
	global_load_dwordx4 v[78:81], v[78:79], off
	s_nop 0
	global_load_dwordx4 v[82:85], v[82:83], off offset:1024

	s_waitcnt lgkmcnt(0)
	v_mfma_f32_16x16x32_bf16 v[2:5], v[2:5], v[154:157], 0
	v_add_co_u32_e32 v86, vcc, s50, v232
	v_mfma_f32_16x16x32_bf16 v[6:9], v[6:9], v[154:157], 0
	ds_read_b128 v[154:157], v237 offset:64
	v_addc_co_u32_e32 v87, vcc, 0, v233, vcc
	s_waitcnt lgkmcnt(0)
	v_mfma_f32_16x16x32_bf16 v[2:5], v[10:13], v[154:157], v[2:5]
	ds_read_b128 v[10:13], v237 offset:128
	global_load_dwordx4 v[86:89], v[86:87], off
	v_mfma_f32_16x16x32_bf16 v[6:9], v[14:17], v[154:157], v[6:9]
	s_waitcnt lgkmcnt(0)
	v_mfma_f32_16x16x32_bf16 v[2:5], v[18:21], v[10:13], v[2:5]
	v_mul_f32_e64 v20, v128, s64
	v_mul_f32_e64 v21, v129, s64
	v_pk_mul_f32 v[18:19], v[126:127], s[64:65] op_sel_hi:[1,0]
	v_mfma_f32_16x16x32_bf16 v[6:9], v[22:25], v[10:13], v[6:9]
	ds_read_b128 v[10:13], v237 offset:192
	s_waitcnt lgkmcnt(0)
	v_mfma_f32_16x16x32_bf16 v[2:5], v[26:29], v[10:13], v[2:5]
	v_mfma_f32_16x16x32_bf16 v[6:9], v[38:41], v[10:13], v[6:9]
	s_nop 6
	v_sub_f32_e32 v5, v240, v5
	v_sub_f32_e32 v4, v239, v4
	v_sub_f32_e32 v3, v238, v3
	v_sub_f32_e32 v2, v193, v2
	v_cvt_pk_bf16_f32 v2, v2, v3
	v_cvt_pk_bf16_f32 v3, v4, v5
	ds_write_b64 v236, v[2:3] offset:4352
	s_waitcnt lgkmcnt(0)
	s_barrier
	ds_read_b128 v[10:13], v235 offset:4352
	ds_read_b128 v[14:17], v235 offset:4416
	s_waitcnt vmcnt(27) lgkmcnt(1)
	v_mfma_f32_16x16x32_bf16 v[2:5], v[130:133], v[10:13], v[6:9]
	s_nop 2
	v_mul_f32_e64 v8, v124, s64
	v_mul_f32_e64 v9, v125, s64
	v_pk_mul_f32 v[6:7], v[122:123], s[64:65] op_sel_hi:[1,0]
	v_readlane_b32 s64, v177, s65
	s_waitcnt vmcnt(26) lgkmcnt(0)
	v_mfma_f32_16x16x32_bf16 v[2:5], v[138:141], v[14:17], v[2:5]
	s_waitcnt vmcnt(25)
	v_mfma_f32_16x16x32_bf16 v[6:9], v[134:137], v[10:13], v[6:9]
	s_waitcnt vmcnt(24)
	v_mfma_f32_16x16x32_bf16 v[154:157], v[142:145], v[14:17], v[6:9]
	s_waitcnt vmcnt(23)
	v_mfma_f32_16x16x32_bf16 v[6:9], v[146:149], v[10:13], v[18:21]
	s_waitcnt vmcnt(22)
	v_mfma_f32_16x16x32_bf16 v[146:149], v[150:153], v[14:17], v[6:9]
	s_nop 5
	v_cvt_pk_bf16_f32 v6, v154, v155
	v_cvt_pk_bf16_f32 v7, v156, v157
	v_cvt_pk_bf16_f32 v8, v146, v147
	v_cvt_pk_bf16_f32 v9, v148, v149
	ds_write2_b64 v234, v[6:7], v[8:9] offset1:4
	v_add_u32_e32 v6, 0xc0, v192
	v_ashrrev_i32_e32 v7, 31, v6
	v_lshlrev_b64 v[6:7], 12, v[6:7]
	v_lshl_add_u64 v[6:7], v[190:191], 0, v[6:7]
	v_add_co_u32_e32 v8, vcc, s30, v6
	global_store_dword v[6:7], v2, off
	s_nop 0
	v_addc_co_u32_e32 v9, vcc, 0, v7, vcc
	v_add_co_u32_e32 v2, vcc, s31, v6
	global_store_dword v[8:9], v3, off offset:-4096
	global_store_dword v[8:9], v4, off
	v_addc_co_u32_e32 v3, vcc, 0, v7, vcc
	global_store_dword v[2:3], v5, off
	v_add_co_u32_e32 v2, vcc, s51, v214
	s_waitcnt lgkmcnt(0)
	s_barrier
	ds_read_b128 v[150:153], v237
	s_nop 0
	v_addc_co_u32_e32 v3, vcc, 0, v215, vcc
	global_load_dwordx4 v[18:21], v[2:3], off
	v_add_co_u32_e32 v2, vcc, s52, v214
	s_nop 1
	v_addc_co_u32_e32 v3, vcc, 0, v215, vcc
	global_load_dwordx4 v[38:41], v[2:3], off
	v_add_co_u32_e32 v2, vcc, s51, v216
	s_nop 1
	v_addc_co_u32_e32 v3, vcc, 0, v217, vcc
	global_load_dwordx4 v[6:9], v[2:3], off
	v_add_co_u32_e32 v2, vcc, s52, v216
	s_nop 1
	v_addc_co_u32_e32 v3, vcc, 0, v217, vcc
	v_add_co_u32_e32 v10, vcc, s51, v218
	global_load_dwordx4 v[2:5], v[2:3], off
	s_nop 0
	v_addc_co_u32_e32 v11, vcc, 0, v219, vcc
	global_load_dwordx4 v[26:29], v[10:11], off
	v_add_co_u32_e32 v10, vcc, s52, v218
	s_nop 1
	v_addc_co_u32_e32 v11, vcc, 0, v219, vcc
	global_load_dwordx4 v[14:17], v[10:11], off
	v_add_co_u32_e32 v10, vcc, s51, v220
	s_nop 1
	v_addc_co_u32_e32 v11, vcc, 0, v221, vcc
	global_load_dwordx4 v[22:25], v[10:11], off
	v_add_co_u32_e32 v10, vcc, s52, v220
	s_nop 1
	v_addc_co_u32_e32 v11, vcc, 0, v221, vcc
	v_add_co_u32_e32 v122, vcc, s53, v222
	global_load_dwordx4 v[10:13], v[10:11], off
	s_nop 0
	v_addc_co_u32_e32 v123, vcc, 0, v223, vcc
	global_load_dword v193, v[122:123], off
	global_load_dword v238, v[122:123], off offset:256
	global_load_dword v239, v[122:123], off offset:512
	global_load_dword v240, v[122:123], off offset:768
	v_add_co_u32_e32 v122, vcc, s54, v224
	s_nop 1
	v_addc_co_u32_e32 v123, vcc, 0, v225, vcc
	v_add_co_u32_e32 v126, vcc, s54, v226
	global_load_dwordx4 v[122:125], v[122:123], off
	s_nop 0
	v_addc_co_u32_e32 v127, vcc, 0, v227, vcc
	v_add_co_u32_e32 v138, vcc, s55, v228
	global_load_dwordx4 v[130:133], v[126:127], off
	s_nop 0
	v_addc_co_u32_e32 v139, vcc, 0, v229, vcc
	v_add_co_u32_e32 v134, vcc, s55, v230
	global_load_dwordx4 v[126:129], v[138:139], off
	s_nop 0
	v_addc_co_u32_e32 v135, vcc, 0, v231, vcc
	global_load_dwordx4 v[134:137], v[134:135], off
	s_nop 0
	global_load_dwordx4 v[138:141], v[138:139], off offset:1024

	s_waitcnt lgkmcnt(0)
	v_mfma_f32_16x16x32_bf16 v[30:33], v[30:33], v[150:153], 0
	v_add_co_u32_e32 v142, vcc, s55, v232
	v_mfma_f32_16x16x32_bf16 v[34:37], v[34:37], v[150:153], 0
	ds_read_b128 v[150:153], v237 offset:64
	v_addc_co_u32_e32 v143, vcc, 0, v233, vcc
	s_waitcnt lgkmcnt(0)
	v_mfma_f32_16x16x32_bf16 v[30:33], v[42:45], v[150:153], v[30:33]
	ds_read_b128 v[42:45], v237 offset:128
	global_load_dwordx4 v[142:145], v[142:143], off
	v_mfma_f32_16x16x32_bf16 v[34:37], v[46:49], v[150:153], v[34:37]
	s_waitcnt lgkmcnt(0)
	v_mfma_f32_16x16x32_bf16 v[30:33], v[50:53], v[42:45], v[30:33]
	v_mul_f32_e64 v52, v148, s64
	v_mul_f32_e64 v53, v149, s64
	v_pk_mul_f32 v[50:51], v[146:147], s[64:65] op_sel_hi:[1,0]
	v_mfma_f32_16x16x32_bf16 v[34:37], v[54:57], v[42:45], v[34:37]
	ds_read_b128 v[42:45], v237 offset:192
	s_waitcnt lgkmcnt(0)
	v_mfma_f32_16x16x32_bf16 v[30:33], v[58:61], v[42:45], v[30:33]
	v_mfma_f32_16x16x32_bf16 v[34:37], v[62:65], v[42:45], v[34:37]
	s_nop 6
	v_sub_f32_e32 v33, v248, v33
	v_sub_f32_e32 v32, v247, v32
	v_sub_f32_e32 v31, v246, v31
	v_sub_f32_e32 v30, v245, v30
	v_cvt_pk_bf16_f32 v30, v30, v31
	v_cvt_pk_bf16_f32 v31, v32, v33
	ds_write_b64 v236, v[30:31] offset:4352
	s_waitcnt lgkmcnt(0)
	s_barrier
	ds_read_b128 v[42:45], v235 offset:4352
	ds_read_b128 v[46:49], v235 offset:4416
	s_waitcnt vmcnt(27) lgkmcnt(1)
	v_mfma_f32_16x16x32_bf16 v[30:33], v[66:69], v[42:45], v[34:37]
	s_nop 2
	v_mul_f32_e64 v36, v156, s64
	v_mul_f32_e64 v37, v157, s64
	v_pk_mul_f32 v[34:35], v[154:155], s[64:65] op_sel_hi:[1,0]
	s_waitcnt vmcnt(26) lgkmcnt(0)
	v_mfma_f32_16x16x32_bf16 v[30:33], v[74:77], v[46:49], v[30:33]
	s_waitcnt vmcnt(25)
	v_mfma_f32_16x16x32_bf16 v[34:37], v[70:73], v[42:45], v[34:37]
	s_waitcnt vmcnt(24)
	v_mfma_f32_16x16x32_bf16 v[146:149], v[78:81], v[46:49], v[34:37]
	s_waitcnt vmcnt(23)
	v_mfma_f32_16x16x32_bf16 v[34:37], v[82:85], v[42:45], v[50:53]
	s_waitcnt vmcnt(22)
	v_mfma_f32_16x16x32_bf16 v[150:153], v[86:89], v[46:49], v[34:37]
	s_nop 5
	v_cvt_pk_bf16_f32 v34, v146, v147
	v_cvt_pk_bf16_f32 v35, v148, v149
	v_cvt_pk_bf16_f32 v36, v150, v151
	v_cvt_pk_bf16_f32 v37, v152, v153
	ds_write2_b64 v234, v[34:35], v[36:37] offset1:4
	v_add_u32_e32 v34, 0x100, v192
	v_ashrrev_i32_e32 v35, 31, v34
	v_lshlrev_b64 v[34:35], 12, v[34:35]
	v_lshl_add_u64 v[34:35], v[190:191], 0, v[34:35]
	v_add_co_u32_e32 v36, vcc, s30, v34
	global_store_dword v[34:35], v30, off
	s_nop 0
	v_addc_co_u32_e32 v37, vcc, 0, v35, vcc
	v_add_co_u32_e32 v30, vcc, s31, v34
	global_store_dword v[36:37], v31, off offset:-4096
	global_store_dword v[36:37], v32, off
	v_addc_co_u32_e32 v31, vcc, 0, v35, vcc
	global_store_dword v[30:31], v33, off
	v_add_co_u32_e32 v30, vcc, s56, v214
	s_waitcnt lgkmcnt(0)
	s_barrier
	s_nop 0
	v_addc_co_u32_e32 v31, vcc, 0, v215, vcc
	v_add_co_u32_e32 v34, vcc, s57, v214
	global_load_dwordx4 v[30:33], v[30:31], off
	s_nop 0
	v_addc_co_u32_e32 v35, vcc, 0, v215, vcc
	v_add_co_u32_e32 v42, vcc, s56, v216
	global_load_dwordx4 v[34:37], v[34:35], off
	s_nop 0
	v_addc_co_u32_e32 v43, vcc, 0, v217, vcc
	global_load_dwordx4 v[46:49], v[42:43], off
	v_add_co_u32_e32 v42, vcc, s57, v216
	s_nop 1
	v_addc_co_u32_e32 v43, vcc, 0, v217, vcc
	ds_read_b128 v[214:217], v237
	global_load_dwordx4 v[50:53], v[42:43], off
	v_add_co_u32_e32 v42, vcc, s56, v218
	s_nop 1
	v_addc_co_u32_e32 v43, vcc, 0, v219, vcc
	v_add_co_u32_e32 v54, vcc, s57, v218
	global_load_dwordx4 v[42:45], v[42:43], off
	s_nop 0
	v_addc_co_u32_e32 v55, vcc, 0, v219, vcc
	v_add_co_u32_e32 v58, vcc, s56, v220
	global_load_dwordx4 v[54:57], v[54:55], off
	s_nop 0
	v_addc_co_u32_e32 v59, vcc, 0, v221, vcc
	v_add_co_u32_e32 v62, vcc, s57, v220
	global_load_dwordx4 v[58:61], v[58:59], off
	s_nop 0
	v_addc_co_u32_e32 v63, vcc, 0, v221, vcc
	v_add_co_u32_e32 v66, vcc, s58, v222
	global_load_dwordx4 v[62:65], v[62:63], off
	s_nop 0
	v_addc_co_u32_e32 v67, vcc, 0, v223, vcc
	global_load_dword v157, v[66:67], off
	global_load_dword v154, v[66:67], off offset:256
	global_load_dword v155, v[66:67], off offset:512
	global_load_dword v156, v[66:67], off offset:768
	v_add_co_u32_e32 v66, vcc, s59, v224
	s_nop 1
	v_addc_co_u32_e32 v67, vcc, 0, v225, vcc
	global_load_dwordx4 v[86:89], v[66:67], off
	v_add_co_u32_e32 v66, vcc, s59, v226
	s_nop 1
	v_addc_co_u32_e32 v67, vcc, 0, v227, vcc
	global_load_dwordx4 v[74:77], v[66:67], off
	v_add_co_u32_e32 v66, vcc, s60, v228
	s_nop 1
	v_addc_co_u32_e32 v67, vcc, 0, v229, vcc
	v_add_co_u32_e32 v68, vcc, s60, v230
	global_load_dwordx4 v[70:73], v[66:67], off
	s_nop 0
	v_addc_co_u32_e32 v69, vcc, 0, v231, vcc
	v_add_co_u32_e32 v78, vcc, s60, v232
	global_load_dwordx4 v[82:85], v[68:69], off
	s_nop 0
	global_load_dwordx4 v[66:69], v[66:67], off offset:1024
	v_addc_co_u32_e32 v79, vcc, 0, v233, vcc
	global_load_dwordx4 v[78:81], v[78:79], off

; DEV void gdn_scan_item(const Params& p, int item, unsigned char* lds) {
;     ...
;     LOAD_E(E0, 0); LOAD_L(L0, 0); LOAD_E(E1, 1);
;     __syncthreads();
;     for (int ch = 0; ch < 30; ch += 6) {
;         SCAN_STEP(E0, E2, L0, L1, ch);     SCAN_STEP(E1, E0, L1, L0, ch + 1); SCAN_STEP(E2, E1, L0, L1, ch + 2);
;         SCAN_STEP(E0, E2, L1, L0, ch + 3); SCAN_STEP(E1, E0, L0, L1, ch + 4); SCAN_STEP(E2, E1, L1, L0, ch + 5);
;     }
;     SCAN_STEP(E0, E2, L0, L1, 30); SCAN_STEP(E1, E0, L1, L0, 31);
	s_waitcnt lgkmcnt(0)
	v_mfma_f32_16x16x32_bf16 v[90:93], v[90:93], v[214:217], 0
	v_mfma_f32_16x16x32_bf16 v[94:97], v[94:97], v[214:217], 0
	ds_read_b128 v[214:217], v237 offset:64
	s_waitcnt lgkmcnt(0)
	v_mfma_f32_16x16x32_bf16 v[90:93], v[98:101], v[214:217], v[90:93]
	ds_read_b128 v[98:101], v237 offset:128
	v_mfma_f32_16x16x32_bf16 v[94:97], v[102:105], v[214:217], v[94:97]
	s_waitcnt lgkmcnt(0)
	v_mfma_f32_16x16x32_bf16 v[90:93], v[106:109], v[98:101], v[90:93]
	v_mul_f32_e64 v108, v152, s62
	v_mul_f32_e64 v109, v153, s62
	v_pk_mul_f32 v[106:107], v[150:151], s[62:63] op_sel_hi:[1,0]
	v_mfma_f32_16x16x32_bf16 v[94:97], v[110:113], v[98:101], v[94:97]
	ds_read_b128 v[98:101], v237 offset:192
	s_waitcnt lgkmcnt(0)
	v_mfma_f32_16x16x32_bf16 v[90:93], v[114:117], v[98:101], v[90:93]
	v_mfma_f32_16x16x32_bf16 v[94:97], v[118:121], v[98:101], v[94:97]
	s_nop 6
	v_sub_f32_e32 v93, v244, v93
	v_sub_f32_e32 v92, v243, v92
	v_sub_f32_e32 v91, v242, v91
	v_sub_f32_e32 v90, v241, v90
	v_cvt_pk_bf16_f32 v90, v90, v91
	v_cvt_pk_bf16_f32 v91, v92, v93
	ds_write_b64 v236, v[90:91] offset:4352
	s_waitcnt lgkmcnt(0)
	s_barrier
	ds_read_b128 v[90:93], v235 offset:4352
	ds_read_b128 v[102:105], v235 offset:4416
	s_waitcnt vmcnt(27) lgkmcnt(1)
	v_mfma_f32_16x16x32_bf16 v[94:97], v[122:125], v[90:93], v[94:97]
	s_waitcnt vmcnt(26) lgkmcnt(0)
	v_mfma_f32_16x16x32_bf16 v[98:101], v[130:133], v[102:105], v[94:97]
	s_nop 5
	v_mul_f32_e64 v96, v148, s62
	v_mul_f32_e64 v97, v149, s62
	v_pk_mul_f32 v[94:95], v[146:147], s[62:63] op_sel_hi:[1,0]
	s_mov_b32 s62, s61
	s_waitcnt vmcnt(25)
	v_mfma_f32_16x16x32_bf16 v[94:97], v[126:129], v[90:93], v[94:97]
	s_waitcnt vmcnt(23)
	v_mfma_f32_16x16x32_bf16 v[90:93], v[138:141], v[90:93], v[106:109]
	v_mfma_f32_16x16x32_bf16 v[94:97], v[134:137], v[102:105], v[94:97]
	s_waitcnt vmcnt(22)
	v_mfma_f32_16x16x32_bf16 v[90:93], v[142:145], v[102:105], v[90:93]
	s_nop 5
	v_cvt_pk_bf16_f32 v102, v94, v95
	v_cvt_pk_bf16_f32 v103, v96, v97
	v_cvt_pk_bf16_f32 v104, v90, v91
	v_cvt_pk_bf16_f32 v105, v92, v93
	ds_write2_b64 v234, v[102:103], v[104:105] offset1:4
	v_add_u32_e32 v102, 0x140, v192
	v_ashrrev_i32_e32 v103, 31, v102
	v_lshlrev_b64 v[102:103], 12, v[102:103]
	v_lshl_add_u64 v[102:103], v[190:191], 0, v[102:103]
	v_add_co_u32_e32 v104, vcc, s30, v102
	global_store_dword v[102:103], v98, off
	s_nop 0
	v_addc_co_u32_e32 v105, vcc, 0, v103, vcc
	v_add_co_u32_e32 v98, vcc, s31, v102
	global_store_dword v[104:105], v99, off offset:-4096
	global_store_dword v[104:105], v100, off
	v_addc_co_u32_e32 v99, vcc, 0, v103, vcc
	global_store_dword v[98:99], v101, off
	s_waitcnt lgkmcnt(0)
	s_barrier
	v_add_u32_e32 v192, 0x180, v192
	s_cbranch_scc1 .LBB0_888
	ds_read_b128 v[98:101], v237
	ds_read_b128 v[102:105], v237 offset:64
	s_add_u32 s8, s12, 0x3e000
	s_addc_u32 s9, s13, 0
	v_lshl_add_u64 v[106:107], s[8:9], 0, v[180:181]
	s_waitcnt lgkmcnt(1)
	v_mfma_f32_16x16x32_bf16 v[18:21], v[18:21], v[98:101], 0
	v_or_b32_e32 v108, 0x400, v184
	v_add3_u32 v1, v1, s24, v179
	s_movk_i32 s13, 0x2000
	v_mfma_f32_16x16x32_bf16 v[38:41], v[38:41], v[98:101], 0
	v_lshl_add_u64 v[98:99], s[8:9], 0, v[182:183]
	s_add_u32 s8, s10, 0x7c000
	s_addc_u32 s9, s11, 0
	s_waitcnt lgkmcnt(0)
	v_mfma_f32_16x16x32_bf16 v[6:9], v[6:9], v[102:105], v[18:21]
	v_lshl_add_u64 v[100:101], s[8:9], 0, v[184:185]
	v_lshl_add_u64 v[110:111], s[8:9], 0, v[188:189]
	s_lshl_b32 s10, s23, 2
	ds_read_b128 v[18:21], v237 offset:128
	v_mfma_f32_16x16x32_bf16 v[2:5], v[2:5], v[102:105], v[38:41]
	s_nop 2
	global_load_dwordx4 v[38:41], v[98:99], off
	s_nop 0
	global_load_dwordx4 v[98:101], v[100:101], off
	ds_read_b128 v[102:105], v237 offset:192
	s_movk_i32 s16, 0x3000
	s_waitcnt lgkmcnt(1)
	v_mfma_f32_16x16x32_bf16 v[6:9], v[26:29], v[18:21], v[6:9]
	global_load_dwordx4 v[26:29], v[106:107], off
	s_nop 0
	global_load_dwordx4 v[106:109], v108, s[8:9]
	v_readlane_b32 s12, v177, 31
	s_lshl_b64 s[4:5], s[4:5], 7
	v_mfma_f32_16x16x32_bf16 v[2:5], v[14:17], v[18:21], v[2:5]
	v_lshl_add_u64 v[18:19], s[8:9], 0, v[186:187]
	global_load_dwordx4 v[14:17], v[110:111], off
	s_nop 0
	global_load_dwordx4 v[18:21], v[18:19], off
	v_readlane_b32 s8, v177, 30
	s_waitcnt lgkmcnt(0)
	v_mfma_f32_16x16x32_bf16 v[6:9], v[22:25], v[102:105], v[6:9]
	v_ashrrev_i32_e32 v177, 31, v176
	v_pk_mul_f32 v[24:25], v[96:97], s[8:9] op_sel_hi:[1,0]
	v_pk_mul_f32 v[22:23], v[94:95], s[8:9] op_sel_hi:[1,0]
	v_mfma_f32_16x16x32_bf16 v[2:5], v[10:13], v[102:105], v[2:5]
	s_nop 3
	v_sub_f32_e32 v9, v240, v9
	v_sub_f32_e32 v8, v239, v8
	v_sub_f32_e32 v7, v238, v7
	v_sub_f32_e32 v6, v193, v6
	v_cvt_pk_bf16_f32 v6, v6, v7
	v_cvt_pk_bf16_f32 v7, v8, v9
	ds_write_b64 v236, v[6:7] offset:4352
	s_waitcnt lgkmcnt(0)
	s_barrier
; DEV void gdn_scan_item(const Params& p, int item, unsigned char* lds) {
;     ...
;     LOAD_E(E0, 0); LOAD_L(L0, 0); LOAD_E(E1, 1);
;     __syncthreads();
;     for (int ch = 0; ch < 30; ch += 6) {
;         SCAN_STEP(E0, E2, L0, L1, ch);     SCAN_STEP(E1, E0, L1, L0, ch + 1); SCAN_STEP(E2, E1, L0, L1, ch + 2);
;         SCAN_STEP(E0, E2, L1, L0, ch + 3); SCAN_STEP(E1, E0, L0, L1, ch + 4); SCAN_STEP(E2, E1, L1, L0, ch + 5);
;     }
;     SCAN_STEP(E0, E2, L0, L1, 30); SCAN_STEP(E1, E0, L1, L0, 31);
;     ...
;     {
;         float* dp = p.out + O_DP + ((size_t)bh * 128 + w * 32 + fq * 4) * 128 + s * 16 + fr;
; #pragma unroll
;         for (int e = 0; e < 4; ++e) { dp[e * 128] = S0[e]; dp[(16 + e) * 128] = S1[e]; }
;     }
;     __syncthreads();
	ds_read_b128 v[6:9], v235 offset:4352
	ds_read_b128 v[10:13], v235 offset:4416
	s_waitcnt vmcnt(13) lgkmcnt(1)
	v_mfma_f32_16x16x32_bf16 v[22:25], v[70:73], v[6:9], v[22:25]
	v_mul_f32_e64 v72, v92, s8
	v_mul_f32_e64 v73, v93, s8
	v_pk_mul_f32 v[70:71], v[90:91], s[8:9] op_sel_hi:[1,0]
	s_mov_b32 s9, 0
	v_mfma_f32_16x16x32_bf16 v[2:5], v[86:89], v[6:9], v[2:5]
	s_lshl_b32 s8, s22, 2
	s_mov_b32 s11, s9
	s_waitcnt vmcnt(11)
	v_mfma_f32_16x16x32_bf16 v[6:9], v[66:69], v[6:9], v[70:73]
	s_waitcnt lgkmcnt(0)
	v_mfma_f32_16x16x32_bf16 v[22:25], v[82:85], v[10:13], v[22:25]
	s_waitcnt vmcnt(10)
	v_mfma_f32_16x16x32_bf16 v[6:9], v[78:81], v[10:13], v[6:9]
	v_mfma_f32_16x16x32_bf16 v[2:5], v[74:77], v[10:13], v[2:5]
	v_add_u32_e32 v10, 0x780, v1
	v_ashrrev_i32_e32 v11, 31, v10
	v_lshlrev_b64 v[10:11], 12, v[10:11]
	v_lshl_add_u64 v[10:11], s[6:7], 0, v[10:11]
	s_nop 0
	v_cvt_pk_bf16_f32 v66, v22, v23
	v_cvt_pk_bf16_f32 v67, v24, v25
	v_cvt_pk_bf16_f32 v68, v6, v7
	v_cvt_pk_bf16_f32 v69, v8, v9
	v_lshl_add_u64 v[10:11], v[10:11], 0, s[8:9]
	ds_write2_b64 v234, v[66:67], v[68:69] offset1:4
	v_lshl_add_u64 v[10:11], v[10:11], 0, s[10:11]
	v_lshlrev_b32_e32 v66, 2, v178
	v_mov_b32_e32 v67, 0
	v_lshl_add_u64 v[10:11], v[10:11], 0, v[66:67]
	v_add_co_u32_e32 v12, vcc, s13, v10
	global_store_dword v[10:11], v2, off
	s_nop 0
	v_addc_co_u32_e32 v13, vcc, 0, v11, vcc
	v_add_co_u32_e32 v2, vcc, s16, v10
	global_store_dword v[12:13], v3, off offset:-4096
	global_store_dword v[12:13], v4, off
	v_addc_co_u32_e32 v3, vcc, 0, v11, vcc
	global_store_dword v[2:3], v5, off
	s_waitcnt lgkmcnt(0)
	s_barrier
	ds_read_b128 v[2:5], v237
	ds_read_b128 v[10:13], v237 offset:64
	s_waitcnt lgkmcnt(1)
	v_mfma_f32_16x16x32_bf16 v[30:33], v[30:33], v[2:5], 0
	v_mul_f32_e64 v24, v24, s12
	v_mul_f32_e64 v25, v25, s12
	v_pk_mul_f32 v[22:23], v[22:23], s[12:13] op_sel_hi:[1,0]
	v_pk_mul_f32 v[8:9], v[8:9], s[12:13] op_sel_hi:[1,0]
	v_mfma_f32_16x16x32_bf16 v[2:5], v[34:37], v[2:5], 0
	v_mul_f32_e64 v6, v6, s12
	v_mul_f32_e64 v7, v7, s12
	s_waitcnt lgkmcnt(0)
	v_mfma_f32_16x16x32_bf16 v[30:33], v[46:49], v[10:13], v[30:33]
	v_mfma_f32_16x16x32_bf16 v[2:5], v[50:53], v[10:13], v[2:5]
	ds_read_b128 v[10:13], v237 offset:128
	ds_read_b128 v[34:37], v237 offset:192
	s_waitcnt lgkmcnt(1)
	v_mfma_f32_16x16x32_bf16 v[30:33], v[42:45], v[10:13], v[30:33]
	v_mfma_f32_16x16x32_bf16 v[2:5], v[54:57], v[10:13], v[2:5]
	s_waitcnt lgkmcnt(0)
	v_mfma_f32_16x16x32_bf16 v[10:13], v[58:61], v[34:37], v[30:33]
	v_mfma_f32_16x16x32_bf16 v[2:5], v[62:65], v[34:37], v[2:5]
	s_nop 6
	v_sub_f32_e32 v13, v156, v13
	v_sub_f32_e32 v12, v155, v12
	v_sub_f32_e32 v11, v154, v11
	v_sub_f32_e32 v10, v157, v10
	v_cvt_pk_bf16_f32 v10, v10, v11
	v_cvt_pk_bf16_f32 v11, v12, v13
	ds_write_b64 v236, v[10:11] offset:4352
	s_waitcnt lgkmcnt(0)
	s_barrier
	ds_read_b128 v[10:13], v235 offset:4352
	ds_read_b128 v[30:33], v235 offset:4416
	s_waitcnt vmcnt(8) lgkmcnt(1)
	v_mfma_f32_16x16x32_bf16 v[22:25], v[98:101], v[10:13], v[22:25]
	s_waitcnt vmcnt(6)
	v_mfma_f32_16x16x32_bf16 v[6:9], v[106:109], v[10:13], v[6:9]
	s_waitcnt vmcnt(5) lgkmcnt(0)
	v_mfma_f32_16x16x32_bf16 v[14:17], v[14:17], v[30:33], v[22:25]
	s_waitcnt vmcnt(4)
	v_mfma_f32_16x16x32_bf16 v[6:9], v[18:21], v[30:33], v[6:9]
	v_mfma_f32_16x16x32_bf16 v[2:5], v[26:29], v[10:13], v[2:5]
	s_nop 4
	v_cvt_pk_bf16_f32 v10, v14, v15
	v_cvt_pk_bf16_f32 v11, v16, v17
	v_cvt_pk_bf16_f32 v12, v6, v7
	v_cvt_pk_bf16_f32 v13, v8, v9
	ds_write2_b64 v234, v[10:11], v[12:13] offset1:4
	v_add_u32_e32 v10, 0x7c0, v1
	v_ashrrev_i32_e32 v11, 31, v10
	v_lshlrev_b64 v[10:11], 12, v[10:11]
	v_lshl_add_u64 v[10:11], s[6:7], 0, v[10:11]
	v_lshl_add_u64 v[10:11], v[10:11], 0, s[8:9]
	v_mfma_f32_16x16x32_bf16 v[2:5], v[38:41], v[30:33], v[2:5]
	v_lshl_add_u64 v[10:11], v[10:11], 0, s[10:11]
	v_lshl_add_u64 v[10:11], v[10:11], 0, v[66:67]
	v_add_co_u32_e32 v12, vcc, s13, v10
	s_nop 1
	v_addc_co_u32_e32 v13, vcc, 0, v11, vcc
	s_nop 1
	global_store_dword v[10:11], v2, off
	v_add_co_u32_e32 v2, vcc, s16, v10
	global_store_dword v[12:13], v3, off offset:-4096
	global_store_dword v[12:13], v4, off
	v_addc_co_u32_e32 v3, vcc, 0, v11, vcc
	global_store_dword v[2:3], v5, off
	s_waitcnt lgkmcnt(0)
	s_barrier
	s_load_dwordx2 s[6:7], s[0:1], 0xc0
	v_lshl_add_u64 v[2:3], s[4:5], 0, v[176:177]
	v_or_b32_e32 v2, v2, v179
	v_lshlrev_b64 v[2:3], 9, v[2:3]
	s_mov_b64 s[4:5], 0x5400000
	s_waitcnt lgkmcnt(0)
	v_lshl_add_u64 v[2:3], s[6:7], 0, v[2:3]
	v_lshl_add_u64 v[2:3], v[2:3], 0, s[10:11]
	v_lshl_add_u64 v[2:3], v[2:3], 0, v[66:67]
	v_lshl_add_u64 v[4:5], v[2:3], 0, s[4:5]
	s_mov_b32 s4, 0x5400000
	v_add_co_u32_e32 v10, vcc, s4, v2
	s_nop 1
	v_addc_co_u32_e32 v11, vcc, 0, v3, vcc
	v_add_co_u32_e32 v2, vcc, 0x5402000, v2
	global_store_dword v[10:11], v14, off
	s_nop 0
	v_addc_co_u32_e32 v3, vcc, 0, v3, vcc
	global_store_dword v[2:3], v6, off
	global_store_dword v[4:5], v15, off offset:512
	global_store_dword v[2:3], v7, off offset:512
	global_store_dword v[4:5], v16, off offset:1024
	global_store_dword v[2:3], v8, off offset:1024
	global_store_dword v[4:5], v17, off offset:1536
	global_store_dword v[2:3], v9, off offset:1536
	s_barrier
